# GU: separate peeled first K-iteration for units that follow an epilogue, with vmcnt(16) on its first two waits so the 8 epilogue stores need not be acknowledged before the K-loop resumes
# baseline (speedup 1.0000x reference)
; #define PG8_BAR __builtin_amdgcn_s_barrier()
; template <class Epi, class Sched, bool ALIGN_EPI = false, bool SP2 = false>
; __device__ __forceinline__ void gemm_phase(PG8_LAS unsigned char* lds, const Gemm g, const Sched& S, const Epi& E) {
;     ...
;         if constexpr (ALIGN_EPI) { if (wr == 1) PG8_BAR; }
.LBB0_189:
	s_bitcmp1_b32 s92, 0
	s_cbranch_scc0 .Lgu_no_restore_bar
	s_barrier

; #define PG8_STAGE(bufoff, gbase, voff) do { _Pragma("unroll") for (int _i = 0; _i < 2; ++_i) \
;         __builtin_amdgcn_global_load_lds((const unsigned*)((const char*)(gbase) + (voff)[_i]), (PG8_LAS unsigned*)(lds + (bufoff) + ldsw + _i * 8192), 16, 0, 0); } while (0)
; #define PG8_LDA(dst, b, h) do { _Pragma("unroll") for (int m = 0; m < 4; ++m) _Pragma("unroll") for (int k = 0; k < 2; ++k) dst[m][k] = *(const PG8_LAS bf16x8*)(lds + PG8_SA(b, h) + aoff + m * 2048 + k * 1024); } while (0)
; #define PG8_LDB(dst, b, h) do { _Pragma("unroll") for (int n = 0; n < 2; ++n) _Pragma("unroll") for (int k = 0; k < 2; ++k) dst[n][k] = *(const PG8_LAS bf16x8*)(lds + PG8_SB(b, h) + boff + n * 2048 + k * 1024); } while (0)
; #define PG8_MMA(ai, bj, At, Bt) do { __builtin_amdgcn_s_setprio(1); _Pragma("unroll") for (int m = 0; m < 4; ++m) _Pragma("unroll") for (int n = 0; n < 2; ++n) _Pragma("unroll") for (int k = 0; k < 2; ++k) \
;         acc[ai][bj][m][n] = mma16<Epi::F16>(Bt[n][k], At[m][k], acc[ai][bj][m][n]); __builtin_amdgcn_s_setprio(0); } while (0)
; #define PG8_WAIT_V(n) asm volatile("s_waitcnt vmcnt(" #n ")" ::: "memory")
; #define PG8_WAIT_L(n) asm volatile("s_waitcnt lgkmcnt(" #n ")" ::: "memory")
; #define PG8_BAR __builtin_amdgcn_s_barrier()
; #define PG8_SCHED __builtin_amdgcn_sched_barrier(0)
; template <class Epi, class Sched, bool ALIGN_EPI = false, bool SP2 = false>
; __device__ __forceinline__ void gemm_phase(PG8_LAS unsigned char* lds, const Gemm g, const Sched& S, const Epi& E) {
;     ...
;             PG8_LDB(B0, 0, 0); PG8_LDB(B1, 0, 1); PG8_SCHED; PG8_LDA(At, 0, 0); PG8_STAGE(PG8_SA(1, 1), a1 + hstep, voffA);
;             PG8_WAIT_V(8); PG8_WAIT_L(0); PG8_BAR; PG8_MMA(0, 0, At, B0); PG8_MMA(0, 1, At, B1); PG8_BAR; PG8_SCHED;
;             PG8_LDA(At, 0, 1); PG8_STAGE(PG8_SB(0, 0), b2, voffB); PG8_STAGE(PG8_SB(0, 1), b2 + hstep, voffB); PG8_STAGE(PG8_SA(0, 0), a2, voffA);
;             PG8_WAIT_V(8); PG8_WAIT_L(0); PG8_BAR; PG8_MMA(1, 0, At, B0); PG8_MMA(1, 1, At, B1); PG8_BAR; PG8_SCHED;
.Lpeel_k1:
	s_cmp_ge_u32 s92, 2
	s_cbranch_scc1 .Lpeel_k1_post
	s_add_u32 s30, s30, 0x80
	s_addc_u32 s31, s31, 0
	s_add_u32 s77, s34, 0x100
	s_addc_u32 s82, s35, 0
	s_mov_b32 s34, 0
	s_add_i32 s84, s34, 2
	s_add_u32 s85, s30, 0x80
	s_addc_u32 s35, s31, 0
	s_add_i32 s92, 0, 0x10000
	s_cmp_eq_u32 s68, s34
	s_cselect_b32 s35, s1, s35
	s_cselect_b32 s34, s0, s85
	v_add_u32_e32 v146, s92, v151
	s_cselect_b32 s97, s57, s82
	s_cselect_b32 s96, s56, s77
	s_add_i32 s85, 0, 0x14000
	ds_read_b128 v[142:145], v146
	ds_read_b128 v[162:165], v146 offset:1024
	ds_read_b128 v[166:169], v146 offset:2048
	ds_read_b128 v[170:173], v146 offset:3072
	v_add_u32_e32 v146, s85, v151
	ds_read_b128 v[174:177], v146
	ds_read_b128 v[178:181], v146 offset:1024
	ds_read_b128 v[182:185], v146 offset:2048
	ds_read_b128 v[186:189], v146 offset:3072
	v_lshl_add_u64 v[148:149], s[30:31], 0, v[138:139]
	s_add_i32 m0, s61, 0xc000
	ds_read_b128 v[190:193], v161
	ds_read_b128 v[194:197], v161 offset:1024
	ds_read_b128 v[198:201], v161 offset:2048
	ds_read_b128 v[202:205], v161 offset:3072
	ds_read_b128 v[212:215], v161 offset:4096
	ds_read_b128 v[216:219], v161 offset:5120
	ds_read_b128 v[220:223], v161 offset:6144
	ds_read_b128 v[224:227], v161 offset:7168
	global_load_lds_dwordx4 v[148:149], off
	v_lshl_add_u64 v[148:149], s[30:31], 0, v[140:141]
	s_add_i32 m0, s61, 0xe000
	s_nop 0
	global_load_lds_dwordx4 v[148:149], off
	s_waitcnt vmcnt(8)
	s_waitcnt lgkmcnt(0)
	s_barrier
	s_setprio 1
	s_waitcnt lgkmcnt(0)
	v_mfma_f32_16x16x32_bf16 v[120:123], v[142:145], v[190:193], 0
	v_mfma_f32_16x16x32_bf16 v[116:119], v[166:169], v[190:193], 0
	v_mfma_f32_16x16x32_bf16 v[108:111], v[142:145], v[198:201], 0
	v_mfma_f32_16x16x32_bf16 v[100:103], v[166:169], v[198:201], 0
	v_mfma_f32_16x16x32_bf16 v[92:95], v[142:145], v[212:215], 0
	v_mfma_f32_16x16x32_bf16 v[84:87], v[166:169], v[212:215], 0
	v_mfma_f32_16x16x32_bf16 v[76:79], v[142:145], v[220:223], 0
	v_mfma_f32_16x16x32_bf16 v[68:71], v[166:169], v[220:223], 0
	v_mfma_f32_16x16x32_bf16 v[120:123], v[162:165], v[194:197], v[120:123]
	v_mfma_f32_16x16x32_bf16 v[116:119], v[170:173], v[194:197], v[116:119]
	v_mfma_f32_16x16x32_bf16 v[108:111], v[162:165], v[202:205], v[108:111]
	v_mfma_f32_16x16x32_bf16 v[100:103], v[170:173], v[202:205], v[100:103]
	v_mfma_f32_16x16x32_bf16 v[92:95], v[162:165], v[216:219], v[92:95]
	v_mfma_f32_16x16x32_bf16 v[84:87], v[170:173], v[216:219], v[84:87]
	v_mfma_f32_16x16x32_bf16 v[76:79], v[162:165], v[224:227], v[76:79]
	v_mfma_f32_16x16x32_bf16 v[68:71], v[170:173], v[224:227], v[68:71]
	s_setprio 0
	s_setprio 1
	v_mfma_f32_16x16x32_bf16 v[124:127], v[174:177], v[190:193], 0
	v_mfma_f32_16x16x32_bf16 v[112:115], v[182:185], v[190:193], 0
	v_mfma_f32_16x16x32_bf16 v[104:107], v[174:177], v[198:201], 0
	v_mfma_f32_16x16x32_bf16 v[96:99], v[182:185], v[198:201], 0
	v_mfma_f32_16x16x32_bf16 v[88:91], v[174:177], v[212:215], 0
	v_mfma_f32_16x16x32_bf16 v[80:83], v[182:185], v[212:215], 0
	v_mfma_f32_16x16x32_bf16 v[72:75], v[174:177], v[220:223], 0
	v_mfma_f32_16x16x32_bf16 v[64:67], v[182:185], v[220:223], 0
	v_mfma_f32_16x16x32_bf16 v[124:127], v[178:181], v[194:197], v[124:127]
	v_mfma_f32_16x16x32_bf16 v[112:115], v[186:189], v[194:197], v[112:115]
	v_mfma_f32_16x16x32_bf16 v[104:107], v[178:181], v[202:205], v[104:107]
	v_mfma_f32_16x16x32_bf16 v[96:99], v[186:189], v[202:205], v[96:99]
	v_mfma_f32_16x16x32_bf16 v[88:91], v[178:181], v[216:219], v[88:91]
	v_mfma_f32_16x16x32_bf16 v[80:83], v[186:189], v[216:219], v[80:83]
	v_mfma_f32_16x16x32_bf16 v[72:75], v[178:181], v[224:227], v[72:75]
	v_mfma_f32_16x16x32_bf16 v[64:67], v[186:189], v[224:227], v[64:67]
	s_setprio 0
	s_barrier
	s_add_i32 s92, s92, s11
	v_lshl_add_u64 v[148:149], s[96:97], 0, v[132:133]
	s_mov_b32 m0, s92
	ds_read_b128 v[190:193], v161 offset:16384
	ds_read_b128 v[194:197], v161 offset:17408
	ds_read_b128 v[198:201], v161 offset:18432
	ds_read_b128 v[202:205], v161 offset:19456
	ds_read_b128 v[212:215], v161 offset:20480
	ds_read_b128 v[216:219], v161 offset:21504
	ds_read_b128 v[220:223], v161 offset:22528
	ds_read_b128 v[224:227], v161 offset:23552
	global_load_lds_dwordx4 v[148:149], off
	s_add_i32 m0, s92, 0x2000
	v_lshl_add_u64 v[152:153], s[96:97], 0, v[128:129]
	s_add_u32 s96, s96, s44
	s_addc_u32 s97, s97, s45
	s_add_i32 s85, s85, s11
	global_load_lds_dwordx4 v[152:153], off
	v_lshl_add_u64 v[206:207], s[96:97], 0, v[132:133]
	s_mov_b32 m0, s85
	v_lshl_add_u64 v[228:229], s[96:97], 0, v[128:129]
	global_load_lds_dwordx4 v[206:207], off
	s_add_i32 m0, s85, 0x2000
	v_lshl_add_u64 v[230:231], s[34:35], 0, v[134:135]
	global_load_lds_dwordx4 v[228:229], off
	s_mov_b32 m0, s61
	v_lshl_add_u64 v[232:233], s[34:35], 0, v[130:131]
	global_load_lds_dwordx4 v[230:231], off
	s_mov_b32 m0, s62
	s_nop 0
	global_load_lds_dwordx4 v[232:233], off
	s_waitcnt vmcnt(8)
	s_waitcnt lgkmcnt(0)
	s_barrier
; #define PG8_STAGE(bufoff, gbase, voff) do { _Pragma("unroll") for (int _i = 0; _i < 2; ++_i) \
;         __builtin_amdgcn_global_load_lds((const unsigned*)((const char*)(gbase) + (voff)[_i]), (PG8_LAS unsigned*)(lds + (bufoff) + ldsw + _i * 8192), 16, 0, 0); } while (0)
; #define PG8_LDA(dst, b, h) do { _Pragma("unroll") for (int m = 0; m < 4; ++m) _Pragma("unroll") for (int k = 0; k < 2; ++k) dst[m][k] = *(const PG8_LAS bf16x8*)(lds + PG8_SA(b, h) + aoff + m * 2048 + k * 1024); } while (0)
; #define PG8_LDB(dst, b, h) do { _Pragma("unroll") for (int n = 0; n < 2; ++n) _Pragma("unroll") for (int k = 0; k < 2; ++k) dst[n][k] = *(const PG8_LAS bf16x8*)(lds + PG8_SB(b, h) + boff + n * 2048 + k * 1024); } while (0)
; #define PG8_MMA(ai, bj, At, Bt) do { __builtin_amdgcn_s_setprio(1); _Pragma("unroll") for (int m = 0; m < 4; ++m) _Pragma("unroll") for (int n = 0; n < 2; ++n) _Pragma("unroll") for (int k = 0; k < 2; ++k) \
;         acc[ai][bj][m][n] = mma16<Epi::F16>(Bt[n][k], At[m][k], acc[ai][bj][m][n]); __builtin_amdgcn_s_setprio(0); } while (0)
; #define PG8_WAIT_V(n) asm volatile("s_waitcnt vmcnt(" #n ")" ::: "memory")
; #define PG8_WAIT_L(n) asm volatile("s_waitcnt lgkmcnt(" #n ")" ::: "memory")
; #define PG8_BAR __builtin_amdgcn_s_barrier()
; #define PG8_SCHED __builtin_amdgcn_sched_barrier(0)
; template <class Epi, class Sched, bool ALIGN_EPI = false, bool SP2 = false>
; __device__ __forceinline__ void gemm_phase(PG8_LAS unsigned char* lds, const Gemm g, const Sched& S, const Epi& E) {
;     ...
;             PG8_WAIT_V(8); PG8_WAIT_L(0); PG8_BAR; PG8_MMA(1, 0, At, B0); PG8_MMA(1, 1, At, B1); PG8_BAR; PG8_SCHED;
;             PG8_LDB(B0, 1, 0); PG8_LDB(B1, 1, 1); PG8_SCHED; PG8_LDA(At, 1, 0); PG8_STAGE(PG8_SA(0, 1), a2 + hstep, voffA);
;             PG8_WAIT_V(8); PG8_WAIT_L(0); PG8_BAR; PG8_MMA(0, 0, At, B0); PG8_MMA(0, 1, At, B1); PG8_BAR; PG8_SCHED;
	s_setprio 1
	s_waitcnt lgkmcnt(0)
	v_mfma_f32_16x16x32_bf16 v[60:63], v[142:145], v[190:193], 0
	v_mfma_f32_16x16x32_bf16 v[52:55], v[166:169], v[190:193], 0
	v_mfma_f32_16x16x32_bf16 v[44:47], v[142:145], v[198:201], 0
	v_mfma_f32_16x16x32_bf16 v[36:39], v[166:169], v[198:201], 0
	v_mfma_f32_16x16x32_bf16 v[28:31], v[142:145], v[212:215], 0
	v_mfma_f32_16x16x32_bf16 v[20:23], v[166:169], v[212:215], 0
	v_mfma_f32_16x16x32_bf16 v[12:15], v[142:145], v[220:223], 0
	v_mfma_f32_16x16x32_bf16 v[4:7], v[166:169], v[220:223], 0
	v_mfma_f32_16x16x32_bf16 v[60:63], v[162:165], v[194:197], v[60:63]
	v_mfma_f32_16x16x32_bf16 v[52:55], v[170:173], v[194:197], v[52:55]
	v_mfma_f32_16x16x32_bf16 v[44:47], v[162:165], v[202:205], v[44:47]
	v_mfma_f32_16x16x32_bf16 v[36:39], v[170:173], v[202:205], v[36:39]
	v_mfma_f32_16x16x32_bf16 v[28:31], v[162:165], v[216:219], v[28:31]
	v_mfma_f32_16x16x32_bf16 v[20:23], v[170:173], v[216:219], v[20:23]
	v_mfma_f32_16x16x32_bf16 v[12:15], v[162:165], v[224:227], v[12:15]
	v_mfma_f32_16x16x32_bf16 v[4:7], v[170:173], v[224:227], v[4:7]
	s_setprio 0
	s_setprio 1
	v_mfma_f32_16x16x32_bf16 v[56:59], v[174:177], v[190:193], 0
	v_mfma_f32_16x16x32_bf16 v[48:51], v[182:185], v[190:193], 0
	v_mfma_f32_16x16x32_bf16 v[40:43], v[174:177], v[198:201], 0
	v_mfma_f32_16x16x32_bf16 v[32:35], v[182:185], v[198:201], 0
	v_mfma_f32_16x16x32_bf16 v[24:27], v[174:177], v[212:215], 0
	v_mfma_f32_16x16x32_bf16 v[16:19], v[182:185], v[212:215], 0
	v_mfma_f32_16x16x32_bf16 v[8:11], v[174:177], v[220:223], 0
	v_mfma_f32_16x16x32_bf16 v[0:3], v[182:185], v[220:223], 0
	v_mfma_f32_16x16x32_bf16 v[56:59], v[178:181], v[194:197], v[56:59]
	v_mfma_f32_16x16x32_bf16 v[48:51], v[186:189], v[194:197], v[48:51]
	v_mfma_f32_16x16x32_bf16 v[40:43], v[178:181], v[202:205], v[40:43]
	v_mfma_f32_16x16x32_bf16 v[32:35], v[186:189], v[202:205], v[32:35]
	v_mfma_f32_16x16x32_bf16 v[24:27], v[178:181], v[216:219], v[24:27]
	v_mfma_f32_16x16x32_bf16 v[16:19], v[186:189], v[216:219], v[16:19]
	v_mfma_f32_16x16x32_bf16 v[8:11], v[178:181], v[224:227], v[8:11]
	v_mfma_f32_16x16x32_bf16 v[0:3], v[186:189], v[224:227], v[0:3]
	s_setprio 0
	s_barrier
	s_add_i32 s85, 0, 0x18000
	v_add_u32_e32 v146, s85, v151
	s_add_i32 s92, 0, 0x1c000
	ds_read_b128 v[142:145], v146
	ds_read_b128 v[162:165], v146 offset:1024
	ds_read_b128 v[166:169], v146 offset:2048
	ds_read_b128 v[170:173], v146 offset:3072
	v_add_u32_e32 v146, s92, v151
	ds_read_b128 v[174:177], v146
	ds_read_b128 v[178:181], v146 offset:1024
	ds_read_b128 v[182:185], v146 offset:2048
	ds_read_b128 v[186:189], v146 offset:3072
	s_add_u32 s34, s34, s44
	s_addc_u32 s35, s35, s45
	s_mov_b32 m0, s63
	v_lshl_add_u64 v[234:235], s[34:35], 0, v[134:135]
	ds_read_b128 v[190:193], v161 offset:32768
	ds_read_b128 v[194:197], v161 offset:33792
	ds_read_b128 v[198:201], v161 offset:34816
	ds_read_b128 v[202:205], v161 offset:35840
	ds_read_b128 v[212:215], v161 offset:36864
	ds_read_b128 v[216:219], v161 offset:37888
	ds_read_b128 v[220:223], v161 offset:38912
	ds_read_b128 v[224:227], v161 offset:39936
	global_load_lds_dwordx4 v[234:235], off
	v_lshl_add_u64 v[234:235], s[34:35], 0, v[130:131]
	s_mov_b32 m0, s64
	s_nop 0
	global_load_lds_dwordx4 v[234:235], off
	s_waitcnt vmcnt(8)
	s_waitcnt lgkmcnt(0)
	s_barrier
	s_setprio 1
	s_waitcnt lgkmcnt(0)
	v_mfma_f32_16x16x32_bf16 v[120:123], v[142:145], v[190:193], v[120:123]
	v_mfma_f32_16x16x32_bf16 v[116:119], v[166:169], v[190:193], v[116:119]
	v_mfma_f32_16x16x32_bf16 v[108:111], v[142:145], v[198:201], v[108:111]
	v_mfma_f32_16x16x32_bf16 v[100:103], v[166:169], v[198:201], v[100:103]
	v_mfma_f32_16x16x32_bf16 v[92:95], v[142:145], v[212:215], v[92:95]
	v_mfma_f32_16x16x32_bf16 v[84:87], v[166:169], v[212:215], v[84:87]
	v_mfma_f32_16x16x32_bf16 v[76:79], v[142:145], v[220:223], v[76:79]
	v_mfma_f32_16x16x32_bf16 v[68:71], v[166:169], v[220:223], v[68:71]
	v_mfma_f32_16x16x32_bf16 v[120:123], v[162:165], v[194:197], v[120:123]
	v_mfma_f32_16x16x32_bf16 v[116:119], v[170:173], v[194:197], v[116:119]
	v_mfma_f32_16x16x32_bf16 v[108:111], v[162:165], v[202:205], v[108:111]
	v_mfma_f32_16x16x32_bf16 v[100:103], v[170:173], v[202:205], v[100:103]
	v_mfma_f32_16x16x32_bf16 v[92:95], v[162:165], v[216:219], v[92:95]
	v_mfma_f32_16x16x32_bf16 v[84:87], v[170:173], v[216:219], v[84:87]
	v_mfma_f32_16x16x32_bf16 v[76:79], v[162:165], v[224:227], v[76:79]
	v_mfma_f32_16x16x32_bf16 v[68:71], v[170:173], v[224:227], v[68:71]
	s_setprio 0
	s_setprio 1
	v_mfma_f32_16x16x32_bf16 v[124:127], v[174:177], v[190:193], v[124:127]
	v_mfma_f32_16x16x32_bf16 v[112:115], v[182:185], v[190:193], v[112:115]
	v_mfma_f32_16x16x32_bf16 v[104:107], v[174:177], v[198:201], v[104:107]
	v_mfma_f32_16x16x32_bf16 v[96:99], v[182:185], v[198:201], v[96:99]
	v_mfma_f32_16x16x32_bf16 v[88:91], v[174:177], v[212:215], v[88:91]
	v_mfma_f32_16x16x32_bf16 v[80:83], v[182:185], v[212:215], v[80:83]
	v_mfma_f32_16x16x32_bf16 v[72:75], v[174:177], v[220:223], v[72:75]
	v_mfma_f32_16x16x32_bf16 v[64:67], v[182:185], v[220:223], v[64:67]
	v_mfma_f32_16x16x32_bf16 v[124:127], v[178:181], v[194:197], v[124:127]
	v_mfma_f32_16x16x32_bf16 v[112:115], v[186:189], v[194:197], v[112:115]
	v_mfma_f32_16x16x32_bf16 v[104:107], v[178:181], v[202:205], v[104:107]
	v_mfma_f32_16x16x32_bf16 v[96:99], v[186:189], v[202:205], v[96:99]
	v_mfma_f32_16x16x32_bf16 v[88:91], v[178:181], v[216:219], v[88:91]
	v_mfma_f32_16x16x32_bf16 v[80:83], v[186:189], v[216:219], v[80:83]
	v_mfma_f32_16x16x32_bf16 v[72:75], v[178:181], v[224:227], v[72:75]
	v_mfma_f32_16x16x32_bf16 v[64:67], v[186:189], v[224:227], v[64:67]
	s_setprio 0
	s_barrier
; #define PG8_STAGE(bufoff, gbase, voff) do { _Pragma("unroll") for (int _i = 0; _i < 2; ++_i) \
;         __builtin_amdgcn_global_load_lds((const unsigned*)((const char*)(gbase) + (voff)[_i]), (PG8_LAS unsigned*)(lds + (bufoff) + ldsw + _i * 8192), 16, 0, 0); } while (0)
; #define PG8_LDA(dst, b, h) do { _Pragma("unroll") for (int m = 0; m < 4; ++m) _Pragma("unroll") for (int k = 0; k < 2; ++k) dst[m][k] = *(const PG8_LAS bf16x8*)(lds + PG8_SA(b, h) + aoff + m * 2048 + k * 1024); } while (0)
; #define PG8_LDB(dst, b, h) do { _Pragma("unroll") for (int n = 0; n < 2; ++n) _Pragma("unroll") for (int k = 0; k < 2; ++k) dst[n][k] = *(const PG8_LAS bf16x8*)(lds + PG8_SB(b, h) + boff + n * 2048 + k * 1024); } while (0)
; #define PG8_MMA(ai, bj, At, Bt) do { __builtin_amdgcn_s_setprio(1); _Pragma("unroll") for (int m = 0; m < 4; ++m) _Pragma("unroll") for (int n = 0; n < 2; ++n) _Pragma("unroll") for (int k = 0; k < 2; ++k) \
;         acc[ai][bj][m][n] = mma16<Epi::F16>(Bt[n][k], At[m][k], acc[ai][bj][m][n]); __builtin_amdgcn_s_setprio(0); } while (0)
; #define PG8_WAIT_V(n) asm volatile("s_waitcnt vmcnt(" #n ")" ::: "memory")
; #define PG8_WAIT_L(n) asm volatile("s_waitcnt lgkmcnt(" #n ")" ::: "memory")
; #define PG8_BAR __builtin_amdgcn_s_barrier()
; #define PG8_SCHED __builtin_amdgcn_sched_barrier(0)
; template <class Epi, class Sched, bool ALIGN_EPI = false, bool SP2 = false>
; __device__ __forceinline__ void gemm_phase(PG8_LAS unsigned char* lds, const Gemm g, const Sched& S, const Epi& E) {
;     ...
;             PG8_LDB(B0, 0, 0); PG8_LDB(B1, 0, 1); PG8_SCHED; PG8_LDA(At, 0, 0); PG8_STAGE(PG8_SA(1, 1), a1 + hstep, voffA);
;             PG8_WAIT_V(8); PG8_WAIT_L(0); PG8_BAR; PG8_MMA(0, 0, At, B0); PG8_MMA(0, 1, At, B1); PG8_BAR; PG8_SCHED;
;     ...
;             PG8_LDA(At, 1, 1); PG8_STAGE(PG8_SB(1, 0), b3, voffB); PG8_STAGE(PG8_SB(1, 1), b3 + hstep, voffB); PG8_STAGE(PG8_SA(1, 0), a3, voffA);
;             PG8_WAIT_V(8); PG8_WAIT_L(0); PG8_BAR; PG8_MMA(1, 0, At, B0); PG8_MMA(1, 1, At, B1); PG8_BAR; PG8_SCHED;
	s_add_i32 s34, s85, s11
	v_lshl_add_u64 v[148:149], v[148:149], 0, s[20:21]
	s_mov_b32 m0, s34
	ds_read_b128 v[190:193], v161 offset:49152
	ds_read_b128 v[194:197], v161 offset:50176
	ds_read_b128 v[198:201], v161 offset:51200
	ds_read_b128 v[202:205], v161 offset:52224
	ds_read_b128 v[212:215], v161 offset:53248
	ds_read_b128 v[216:219], v161 offset:54272
	ds_read_b128 v[220:223], v161 offset:55296
	ds_read_b128 v[224:227], v161 offset:56320
	global_load_lds_dwordx4 v[148:149], off
	v_lshl_add_u64 v[148:149], v[152:153], 0, s[20:21]
	s_add_i32 m0, s34, 0x2000
	s_add_i32 s34, s92, s11
	global_load_lds_dwordx4 v[148:149], off
	v_lshl_add_u64 v[148:149], v[206:207], 0, s[20:21]
	s_mov_b32 m0, s34
	s_nop 0
	global_load_lds_dwordx4 v[148:149], off
	v_lshl_add_u64 v[148:149], v[228:229], 0, s[20:21]
	s_add_i32 m0, s34, 0x2000
	s_nop 0
	global_load_lds_dwordx4 v[148:149], off
	v_lshl_add_u64 v[148:149], v[230:231], 0, s[20:21]
	s_mov_b32 m0, s65
	s_nop 0
	global_load_lds_dwordx4 v[148:149], off
	v_lshl_add_u64 v[148:149], v[232:233], 0, s[20:21]
	s_mov_b32 m0, s66
	s_nop 0
	global_load_lds_dwordx4 v[148:149], off
	s_waitcnt vmcnt(8)
	s_waitcnt lgkmcnt(0)
	s_barrier
	s_setprio 1
	s_waitcnt lgkmcnt(0)
	v_mfma_f32_16x16x32_bf16 v[60:63], v[142:145], v[190:193], v[60:63]
	v_mfma_f32_16x16x32_bf16 v[52:55], v[166:169], v[190:193], v[52:55]
	v_mfma_f32_16x16x32_bf16 v[44:47], v[142:145], v[198:201], v[44:47]
	v_mfma_f32_16x16x32_bf16 v[36:39], v[166:169], v[198:201], v[36:39]
	v_mfma_f32_16x16x32_bf16 v[28:31], v[142:145], v[212:215], v[28:31]
	v_mfma_f32_16x16x32_bf16 v[20:23], v[166:169], v[212:215], v[20:23]
	v_mfma_f32_16x16x32_bf16 v[12:15], v[142:145], v[220:223], v[12:15]
	v_mfma_f32_16x16x32_bf16 v[4:7], v[166:169], v[220:223], v[4:7]
	v_mfma_f32_16x16x32_bf16 v[60:63], v[162:165], v[194:197], v[60:63]
	v_mfma_f32_16x16x32_bf16 v[52:55], v[170:173], v[194:197], v[52:55]
	v_mfma_f32_16x16x32_bf16 v[44:47], v[162:165], v[202:205], v[44:47]
	v_mfma_f32_16x16x32_bf16 v[36:39], v[170:173], v[202:205], v[36:39]
	v_mfma_f32_16x16x32_bf16 v[28:31], v[162:165], v[216:219], v[28:31]
	v_mfma_f32_16x16x32_bf16 v[20:23], v[170:173], v[216:219], v[20:23]
	v_mfma_f32_16x16x32_bf16 v[12:15], v[162:165], v[224:227], v[12:15]
	v_mfma_f32_16x16x32_bf16 v[4:7], v[170:173], v[224:227], v[4:7]
	s_setprio 0
	s_setprio 1
	v_mfma_f32_16x16x32_bf16 v[56:59], v[174:177], v[190:193], v[56:59]
	v_mfma_f32_16x16x32_bf16 v[48:51], v[182:185], v[190:193], v[48:51]
	v_mfma_f32_16x16x32_bf16 v[40:43], v[174:177], v[198:201], v[40:43]
	v_mfma_f32_16x16x32_bf16 v[32:35], v[182:185], v[198:201], v[32:35]
	v_mfma_f32_16x16x32_bf16 v[24:27], v[174:177], v[212:215], v[24:27]
	v_mfma_f32_16x16x32_bf16 v[16:19], v[182:185], v[212:215], v[16:19]
	v_mfma_f32_16x16x32_bf16 v[8:11], v[174:177], v[220:223], v[8:11]
	v_mfma_f32_16x16x32_bf16 v[0:3], v[182:185], v[220:223], v[0:3]
	v_mfma_f32_16x16x32_bf16 v[56:59], v[178:181], v[194:197], v[56:59]
	v_mfma_f32_16x16x32_bf16 v[48:51], v[186:189], v[194:197], v[48:51]
	v_mfma_f32_16x16x32_bf16 v[40:43], v[178:181], v[202:205], v[40:43]
	v_mfma_f32_16x16x32_bf16 v[32:35], v[186:189], v[202:205], v[32:35]
	v_mfma_f32_16x16x32_bf16 v[24:27], v[178:181], v[216:219], v[24:27]
	v_mfma_f32_16x16x32_bf16 v[16:19], v[186:189], v[216:219], v[16:19]
	v_mfma_f32_16x16x32_bf16 v[8:11], v[178:181], v[224:227], v[8:11]
	v_mfma_f32_16x16x32_bf16 v[0:3], v[186:189], v[224:227], v[0:3]
	s_setprio 0
	s_barrier
	s_add_u32 s30, s30, 0x100
	s_addc_u32 s31, s31, 0
	s_add_u32 s77, s77, 0x100
	s_addc_u32 s82, s82, 0
	s_cmp_ge_i32 s84, s67
	s_mov_b32 s34, s84
	s_cbranch_scc0 .LBB0_191
	s_branch .LBB0_192
.Lpeel_k1_post:
	s_add_u32 s30, s30, 0x80
	s_addc_u32 s31, s31, 0
	s_add_u32 s77, s34, 0x100
	s_addc_u32 s82, s35, 0
	s_mov_b32 s34, 0
	s_add_i32 s84, s34, 2
	s_add_u32 s85, s30, 0x80
	s_addc_u32 s35, s31, 0
	s_add_i32 s92, 0, 0x10000
	s_cmp_eq_u32 s68, s34
	s_cselect_b32 s35, s1, s35
	s_cselect_b32 s34, s0, s85
	v_add_u32_e32 v146, s92, v151
	s_cselect_b32 s97, s57, s82
	s_cselect_b32 s96, s56, s77
	s_add_i32 s85, 0, 0x14000
	ds_read_b128 v[142:145], v146
	ds_read_b128 v[162:165], v146 offset:1024
	ds_read_b128 v[166:169], v146 offset:2048
	ds_read_b128 v[170:173], v146 offset:3072
	v_add_u32_e32 v146, s85, v151
	ds_read_b128 v[174:177], v146
	ds_read_b128 v[178:181], v146 offset:1024
	ds_read_b128 v[182:185], v146 offset:2048
	ds_read_b128 v[186:189], v146 offset:3072
	v_lshl_add_u64 v[148:149], s[30:31], 0, v[138:139]
	s_add_i32 m0, s61, 0xc000
	ds_read_b128 v[190:193], v161
	ds_read_b128 v[194:197], v161 offset:1024
	ds_read_b128 v[198:201], v161 offset:2048
	ds_read_b128 v[202:205], v161 offset:3072
	ds_read_b128 v[212:215], v161 offset:4096
	ds_read_b128 v[216:219], v161 offset:5120
	ds_read_b128 v[220:223], v161 offset:6144
	ds_read_b128 v[224:227], v161 offset:7168
	global_load_lds_dwordx4 v[148:149], off
	v_lshl_add_u64 v[148:149], s[30:31], 0, v[140:141]
	s_add_i32 m0, s61, 0xe000
	s_nop 0
	global_load_lds_dwordx4 v[148:149], off
	s_waitcnt vmcnt(16)
	s_waitcnt lgkmcnt(0)
	s_barrier
; #define PG8_STAGE(bufoff, gbase, voff) do { _Pragma("unroll") for (int _i = 0; _i < 2; ++_i) \
;         __builtin_amdgcn_global_load_lds((const unsigned*)((const char*)(gbase) + (voff)[_i]), (PG8_LAS unsigned*)(lds + (bufoff) + ldsw + _i * 8192), 16, 0, 0); } while (0)
; #define PG8_LDA(dst, b, h) do { _Pragma("unroll") for (int m = 0; m < 4; ++m) _Pragma("unroll") for (int k = 0; k < 2; ++k) dst[m][k] = *(const PG8_LAS bf16x8*)(lds + PG8_SA(b, h) + aoff + m * 2048 + k * 1024); } while (0)
; #define PG8_MMA(ai, bj, At, Bt) do { __builtin_amdgcn_s_setprio(1); _Pragma("unroll") for (int m = 0; m < 4; ++m) _Pragma("unroll") for (int n = 0; n < 2; ++n) _Pragma("unroll") for (int k = 0; k < 2; ++k) \
;         acc[ai][bj][m][n] = mma16<Epi::F16>(Bt[n][k], At[m][k], acc[ai][bj][m][n]); __builtin_amdgcn_s_setprio(0); } while (0)
; #define PG8_WAIT_V(n) asm volatile("s_waitcnt vmcnt(" #n ")" ::: "memory")
; #define PG8_WAIT_L(n) asm volatile("s_waitcnt lgkmcnt(" #n ")" ::: "memory")
; #define PG8_BAR __builtin_amdgcn_s_barrier()
; #define PG8_SCHED __builtin_amdgcn_sched_barrier(0)
; template <class Epi, class Sched, bool ALIGN_EPI = false, bool SP2 = false>
; __device__ __forceinline__ void gemm_phase(PG8_LAS unsigned char* lds, const Gemm g, const Sched& S, const Epi& E) {
;     ...
;             PG8_WAIT_V(8); PG8_WAIT_L(0); PG8_BAR; PG8_MMA(0, 0, At, B0); PG8_MMA(0, 1, At, B1); PG8_BAR; PG8_SCHED;
;             PG8_LDA(At, 0, 1); PG8_STAGE(PG8_SB(0, 0), b2, voffB); PG8_STAGE(PG8_SB(0, 1), b2 + hstep, voffB); PG8_STAGE(PG8_SA(0, 0), a2, voffA);
;             PG8_WAIT_V(8); PG8_WAIT_L(0); PG8_BAR; PG8_MMA(1, 0, At, B0); PG8_MMA(1, 1, At, B1); PG8_BAR; PG8_SCHED;
	s_setprio 1
	s_waitcnt lgkmcnt(0)
	v_mfma_f32_16x16x32_bf16 v[120:123], v[142:145], v[190:193], 0
	v_mfma_f32_16x16x32_bf16 v[116:119], v[166:169], v[190:193], 0
	v_mfma_f32_16x16x32_bf16 v[108:111], v[142:145], v[198:201], 0
	v_mfma_f32_16x16x32_bf16 v[100:103], v[166:169], v[198:201], 0
	v_mfma_f32_16x16x32_bf16 v[92:95], v[142:145], v[212:215], 0
	v_mfma_f32_16x16x32_bf16 v[84:87], v[166:169], v[212:215], 0
	v_mfma_f32_16x16x32_bf16 v[76:79], v[142:145], v[220:223], 0
	v_mfma_f32_16x16x32_bf16 v[68:71], v[166:169], v[220:223], 0
	v_mfma_f32_16x16x32_bf16 v[120:123], v[162:165], v[194:197], v[120:123]
	v_mfma_f32_16x16x32_bf16 v[116:119], v[170:173], v[194:197], v[116:119]
	v_mfma_f32_16x16x32_bf16 v[108:111], v[162:165], v[202:205], v[108:111]
	v_mfma_f32_16x16x32_bf16 v[100:103], v[170:173], v[202:205], v[100:103]
	v_mfma_f32_16x16x32_bf16 v[92:95], v[162:165], v[216:219], v[92:95]
	v_mfma_f32_16x16x32_bf16 v[84:87], v[170:173], v[216:219], v[84:87]
	v_mfma_f32_16x16x32_bf16 v[76:79], v[162:165], v[224:227], v[76:79]
	v_mfma_f32_16x16x32_bf16 v[68:71], v[170:173], v[224:227], v[68:71]
	s_setprio 0
	s_setprio 1
	v_mfma_f32_16x16x32_bf16 v[124:127], v[174:177], v[190:193], 0
	v_mfma_f32_16x16x32_bf16 v[112:115], v[182:185], v[190:193], 0
	v_mfma_f32_16x16x32_bf16 v[104:107], v[174:177], v[198:201], 0
	v_mfma_f32_16x16x32_bf16 v[96:99], v[182:185], v[198:201], 0
	v_mfma_f32_16x16x32_bf16 v[88:91], v[174:177], v[212:215], 0
	v_mfma_f32_16x16x32_bf16 v[80:83], v[182:185], v[212:215], 0
	v_mfma_f32_16x16x32_bf16 v[72:75], v[174:177], v[220:223], 0
	v_mfma_f32_16x16x32_bf16 v[64:67], v[182:185], v[220:223], 0
	v_mfma_f32_16x16x32_bf16 v[124:127], v[178:181], v[194:197], v[124:127]
	v_mfma_f32_16x16x32_bf16 v[112:115], v[186:189], v[194:197], v[112:115]
	v_mfma_f32_16x16x32_bf16 v[104:107], v[178:181], v[202:205], v[104:107]
	v_mfma_f32_16x16x32_bf16 v[96:99], v[186:189], v[202:205], v[96:99]
	v_mfma_f32_16x16x32_bf16 v[88:91], v[178:181], v[216:219], v[88:91]
	v_mfma_f32_16x16x32_bf16 v[80:83], v[186:189], v[216:219], v[80:83]
	v_mfma_f32_16x16x32_bf16 v[72:75], v[178:181], v[224:227], v[72:75]
	v_mfma_f32_16x16x32_bf16 v[64:67], v[186:189], v[224:227], v[64:67]
	s_setprio 0
	s_barrier
	s_add_i32 s92, s92, s11
	v_lshl_add_u64 v[148:149], s[96:97], 0, v[132:133]
	s_mov_b32 m0, s92
	ds_read_b128 v[190:193], v161 offset:16384
	ds_read_b128 v[194:197], v161 offset:17408
	ds_read_b128 v[198:201], v161 offset:18432
	ds_read_b128 v[202:205], v161 offset:19456
	ds_read_b128 v[212:215], v161 offset:20480
	ds_read_b128 v[216:219], v161 offset:21504
	ds_read_b128 v[220:223], v161 offset:22528
	ds_read_b128 v[224:227], v161 offset:23552
	global_load_lds_dwordx4 v[148:149], off
	s_add_i32 m0, s92, 0x2000
	v_lshl_add_u64 v[152:153], s[96:97], 0, v[128:129]
	s_add_u32 s96, s96, s44
	s_addc_u32 s97, s97, s45
	s_add_i32 s85, s85, s11
	global_load_lds_dwordx4 v[152:153], off
	v_lshl_add_u64 v[206:207], s[96:97], 0, v[132:133]
	s_mov_b32 m0, s85
	v_lshl_add_u64 v[228:229], s[96:97], 0, v[128:129]
	global_load_lds_dwordx4 v[206:207], off
	s_add_i32 m0, s85, 0x2000
	v_lshl_add_u64 v[230:231], s[34:35], 0, v[134:135]
	global_load_lds_dwordx4 v[228:229], off
	s_mov_b32 m0, s61
	v_lshl_add_u64 v[232:233], s[34:35], 0, v[130:131]
	global_load_lds_dwordx4 v[230:231], off
	s_mov_b32 m0, s62
	s_nop 0
	global_load_lds_dwordx4 v[232:233], off
	s_waitcnt vmcnt(16)
	s_waitcnt lgkmcnt(0)
	s_barrier
	s_setprio 1
	s_waitcnt lgkmcnt(0)
	v_mfma_f32_16x16x32_bf16 v[60:63], v[142:145], v[190:193], 0
	v_mfma_f32_16x16x32_bf16 v[52:55], v[166:169], v[190:193], 0
	v_mfma_f32_16x16x32_bf16 v[44:47], v[142:145], v[198:201], 0
	v_mfma_f32_16x16x32_bf16 v[36:39], v[166:169], v[198:201], 0
	v_mfma_f32_16x16x32_bf16 v[28:31], v[142:145], v[212:215], 0
	v_mfma_f32_16x16x32_bf16 v[20:23], v[166:169], v[212:215], 0
	v_mfma_f32_16x16x32_bf16 v[12:15], v[142:145], v[220:223], 0
	v_mfma_f32_16x16x32_bf16 v[4:7], v[166:169], v[220:223], 0
	v_mfma_f32_16x16x32_bf16 v[60:63], v[162:165], v[194:197], v[60:63]
	v_mfma_f32_16x16x32_bf16 v[52:55], v[170:173], v[194:197], v[52:55]
	v_mfma_f32_16x16x32_bf16 v[44:47], v[162:165], v[202:205], v[44:47]
	v_mfma_f32_16x16x32_bf16 v[36:39], v[170:173], v[202:205], v[36:39]
	v_mfma_f32_16x16x32_bf16 v[28:31], v[162:165], v[216:219], v[28:31]
	v_mfma_f32_16x16x32_bf16 v[20:23], v[170:173], v[216:219], v[20:23]
	v_mfma_f32_16x16x32_bf16 v[12:15], v[162:165], v[224:227], v[12:15]
	v_mfma_f32_16x16x32_bf16 v[4:7], v[170:173], v[224:227], v[4:7]
	s_setprio 0
	s_setprio 1
	v_mfma_f32_16x16x32_bf16 v[56:59], v[174:177], v[190:193], 0
	v_mfma_f32_16x16x32_bf16 v[48:51], v[182:185], v[190:193], 0
	v_mfma_f32_16x16x32_bf16 v[40:43], v[174:177], v[198:201], 0
	v_mfma_f32_16x16x32_bf16 v[32:35], v[182:185], v[198:201], 0
	v_mfma_f32_16x16x32_bf16 v[24:27], v[174:177], v[212:215], 0
	v_mfma_f32_16x16x32_bf16 v[16:19], v[182:185], v[212:215], 0
	v_mfma_f32_16x16x32_bf16 v[8:11], v[174:177], v[220:223], 0
	v_mfma_f32_16x16x32_bf16 v[0:3], v[182:185], v[220:223], 0
	v_mfma_f32_16x16x32_bf16 v[56:59], v[178:181], v[194:197], v[56:59]
	v_mfma_f32_16x16x32_bf16 v[48:51], v[186:189], v[194:197], v[48:51]
	v_mfma_f32_16x16x32_bf16 v[40:43], v[178:181], v[202:205], v[40:43]
	v_mfma_f32_16x16x32_bf16 v[32:35], v[186:189], v[202:205], v[32:35]
	v_mfma_f32_16x16x32_bf16 v[24:27], v[178:181], v[216:219], v[24:27]
	v_mfma_f32_16x16x32_bf16 v[16:19], v[186:189], v[216:219], v[16:19]
	v_mfma_f32_16x16x32_bf16 v[8:11], v[178:181], v[224:227], v[8:11]
	v_mfma_f32_16x16x32_bf16 v[0:3], v[186:189], v[224:227], v[0:3]
	s_setprio 0
	s_barrier
; #define PG8_STAGE(bufoff, gbase, voff) do { _Pragma("unroll") for (int _i = 0; _i < 2; ++_i) \
;         __builtin_amdgcn_global_load_lds((const unsigned*)((const char*)(gbase) + (voff)[_i]), (PG8_LAS unsigned*)(lds + (bufoff) + ldsw + _i * 8192), 16, 0, 0); } while (0)
; #define PG8_LDA(dst, b, h) do { _Pragma("unroll") for (int m = 0; m < 4; ++m) _Pragma("unroll") for (int k = 0; k < 2; ++k) dst[m][k] = *(const PG8_LAS bf16x8*)(lds + PG8_SA(b, h) + aoff + m * 2048 + k * 1024); } while (0)
; #define PG8_LDB(dst, b, h) do { _Pragma("unroll") for (int n = 0; n < 2; ++n) _Pragma("unroll") for (int k = 0; k < 2; ++k) dst[n][k] = *(const PG8_LAS bf16x8*)(lds + PG8_SB(b, h) + boff + n * 2048 + k * 1024); } while (0)
; #define PG8_MMA(ai, bj, At, Bt) do { __builtin_amdgcn_s_setprio(1); _Pragma("unroll") for (int m = 0; m < 4; ++m) _Pragma("unroll") for (int n = 0; n < 2; ++n) _Pragma("unroll") for (int k = 0; k < 2; ++k) \
;         acc[ai][bj][m][n] = mma16<Epi::F16>(Bt[n][k], At[m][k], acc[ai][bj][m][n]); __builtin_amdgcn_s_setprio(0); } while (0)
; #define PG8_WAIT_V(n) asm volatile("s_waitcnt vmcnt(" #n ")" ::: "memory")
; #define PG8_WAIT_L(n) asm volatile("s_waitcnt lgkmcnt(" #n ")" ::: "memory")
; #define PG8_BAR __builtin_amdgcn_s_barrier()
; #define PG8_SCHED __builtin_amdgcn_sched_barrier(0)
; template <class Epi, class Sched, bool ALIGN_EPI = false, bool SP2 = false>
; __device__ __forceinline__ void gemm_phase(PG8_LAS unsigned char* lds, const Gemm g, const Sched& S, const Epi& E) {
;     ...
;             PG8_LDB(B0, 1, 0); PG8_LDB(B1, 1, 1); PG8_SCHED; PG8_LDA(At, 1, 0); PG8_STAGE(PG8_SA(0, 1), a2 + hstep, voffA);
;             PG8_WAIT_V(8); PG8_WAIT_L(0); PG8_BAR; PG8_MMA(0, 0, At, B0); PG8_MMA(0, 1, At, B1); PG8_BAR; PG8_SCHED;
	s_add_i32 s85, 0, 0x18000
	v_add_u32_e32 v146, s85, v151
	s_add_i32 s92, 0, 0x1c000
	ds_read_b128 v[142:145], v146
	ds_read_b128 v[162:165], v146 offset:1024
	ds_read_b128 v[166:169], v146 offset:2048
	ds_read_b128 v[170:173], v146 offset:3072
	v_add_u32_e32 v146, s92, v151
	ds_read_b128 v[174:177], v146
	ds_read_b128 v[178:181], v146 offset:1024
	ds_read_b128 v[182:185], v146 offset:2048
	ds_read_b128 v[186:189], v146 offset:3072
	s_add_u32 s34, s34, s44
	s_addc_u32 s35, s35, s45
	s_mov_b32 m0, s63
	v_lshl_add_u64 v[234:235], s[34:35], 0, v[134:135]
	ds_read_b128 v[190:193], v161 offset:32768
	ds_read_b128 v[194:197], v161 offset:33792
	ds_read_b128 v[198:201], v161 offset:34816
	ds_read_b128 v[202:205], v161 offset:35840
	ds_read_b128 v[212:215], v161 offset:36864
	ds_read_b128 v[216:219], v161 offset:37888
	ds_read_b128 v[220:223], v161 offset:38912
	ds_read_b128 v[224:227], v161 offset:39936
	global_load_lds_dwordx4 v[234:235], off
	v_lshl_add_u64 v[234:235], s[34:35], 0, v[130:131]
	s_mov_b32 m0, s64
	s_nop 0
	global_load_lds_dwordx4 v[234:235], off
	s_waitcnt vmcnt(8)
	s_waitcnt lgkmcnt(0)
	s_barrier
	s_setprio 1
	s_waitcnt lgkmcnt(0)
	v_mfma_f32_16x16x32_bf16 v[120:123], v[142:145], v[190:193], v[120:123]
	v_mfma_f32_16x16x32_bf16 v[116:119], v[166:169], v[190:193], v[116:119]
	v_mfma_f32_16x16x32_bf16 v[108:111], v[142:145], v[198:201], v[108:111]
	v_mfma_f32_16x16x32_bf16 v[100:103], v[166:169], v[198:201], v[100:103]
	v_mfma_f32_16x16x32_bf16 v[92:95], v[142:145], v[212:215], v[92:95]
	v_mfma_f32_16x16x32_bf16 v[84:87], v[166:169], v[212:215], v[84:87]
	v_mfma_f32_16x16x32_bf16 v[76:79], v[142:145], v[220:223], v[76:79]
	v_mfma_f32_16x16x32_bf16 v[68:71], v[166:169], v[220:223], v[68:71]
	v_mfma_f32_16x16x32_bf16 v[120:123], v[162:165], v[194:197], v[120:123]
	v_mfma_f32_16x16x32_bf16 v[116:119], v[170:173], v[194:197], v[116:119]
	v_mfma_f32_16x16x32_bf16 v[108:111], v[162:165], v[202:205], v[108:111]
	v_mfma_f32_16x16x32_bf16 v[100:103], v[170:173], v[202:205], v[100:103]
	v_mfma_f32_16x16x32_bf16 v[92:95], v[162:165], v[216:219], v[92:95]
	v_mfma_f32_16x16x32_bf16 v[84:87], v[170:173], v[216:219], v[84:87]
	v_mfma_f32_16x16x32_bf16 v[76:79], v[162:165], v[224:227], v[76:79]
	v_mfma_f32_16x16x32_bf16 v[68:71], v[170:173], v[224:227], v[68:71]
	s_setprio 0
	s_setprio 1
	v_mfma_f32_16x16x32_bf16 v[124:127], v[174:177], v[190:193], v[124:127]
	v_mfma_f32_16x16x32_bf16 v[112:115], v[182:185], v[190:193], v[112:115]
	v_mfma_f32_16x16x32_bf16 v[104:107], v[174:177], v[198:201], v[104:107]
	v_mfma_f32_16x16x32_bf16 v[96:99], v[182:185], v[198:201], v[96:99]
	v_mfma_f32_16x16x32_bf16 v[88:91], v[174:177], v[212:215], v[88:91]
	v_mfma_f32_16x16x32_bf16 v[80:83], v[182:185], v[212:215], v[80:83]
	v_mfma_f32_16x16x32_bf16 v[72:75], v[174:177], v[220:223], v[72:75]
	v_mfma_f32_16x16x32_bf16 v[64:67], v[182:185], v[220:223], v[64:67]
	v_mfma_f32_16x16x32_bf16 v[124:127], v[178:181], v[194:197], v[124:127]
	v_mfma_f32_16x16x32_bf16 v[112:115], v[186:189], v[194:197], v[112:115]
	v_mfma_f32_16x16x32_bf16 v[104:107], v[178:181], v[202:205], v[104:107]
	v_mfma_f32_16x16x32_bf16 v[96:99], v[186:189], v[202:205], v[96:99]
	v_mfma_f32_16x16x32_bf16 v[88:91], v[178:181], v[216:219], v[88:91]
	v_mfma_f32_16x16x32_bf16 v[80:83], v[186:189], v[216:219], v[80:83]
	v_mfma_f32_16x16x32_bf16 v[72:75], v[178:181], v[224:227], v[72:75]
	v_mfma_f32_16x16x32_bf16 v[64:67], v[186:189], v[224:227], v[64:67]
	s_setprio 0
	s_barrier
; #define PG8_STAGE(bufoff, gbase, voff) do { _Pragma("unroll") for (int _i = 0; _i < 2; ++_i) \
;         __builtin_amdgcn_global_load_lds((const unsigned*)((const char*)(gbase) + (voff)[_i]), (PG8_LAS unsigned*)(lds + (bufoff) + ldsw + _i * 8192), 16, 0, 0); } while (0)
; #define PG8_LDA(dst, b, h) do { _Pragma("unroll") for (int m = 0; m < 4; ++m) _Pragma("unroll") for (int k = 0; k < 2; ++k) dst[m][k] = *(const PG8_LAS bf16x8*)(lds + PG8_SA(b, h) + aoff + m * 2048 + k * 1024); } while (0)
; #define PG8_MMA(ai, bj, At, Bt) do { __builtin_amdgcn_s_setprio(1); _Pragma("unroll") for (int m = 0; m < 4; ++m) _Pragma("unroll") for (int n = 0; n < 2; ++n) _Pragma("unroll") for (int k = 0; k < 2; ++k) \
;         acc[ai][bj][m][n] = mma16<Epi::F16>(Bt[n][k], At[m][k], acc[ai][bj][m][n]); __builtin_amdgcn_s_setprio(0); } while (0)
; #define PG8_WAIT_V(n) asm volatile("s_waitcnt vmcnt(" #n ")" ::: "memory")
; #define PG8_WAIT_L(n) asm volatile("s_waitcnt lgkmcnt(" #n ")" ::: "memory")
; #define PG8_BAR __builtin_amdgcn_s_barrier()
; #define PG8_SCHED __builtin_amdgcn_sched_barrier(0)
; template <class Epi, class Sched, bool ALIGN_EPI = false, bool SP2 = false>
; __device__ __forceinline__ void gemm_phase(PG8_LAS unsigned char* lds, const Gemm g, const Sched& S, const Epi& E) {
;     ...
;             PG8_LDA(At, 1, 1); PG8_STAGE(PG8_SB(1, 0), b3, voffB); PG8_STAGE(PG8_SB(1, 1), b3 + hstep, voffB); PG8_STAGE(PG8_SA(1, 0), a3, voffA);
;             PG8_WAIT_V(8); PG8_WAIT_L(0); PG8_BAR; PG8_MMA(1, 0, At, B0); PG8_MMA(1, 1, At, B1); PG8_BAR; PG8_SCHED;
	s_add_i32 s34, s85, s11
	v_lshl_add_u64 v[148:149], v[148:149], 0, s[20:21]
	s_mov_b32 m0, s34
	ds_read_b128 v[190:193], v161 offset:49152
	ds_read_b128 v[194:197], v161 offset:50176
	ds_read_b128 v[198:201], v161 offset:51200
	ds_read_b128 v[202:205], v161 offset:52224
	ds_read_b128 v[212:215], v161 offset:53248
	ds_read_b128 v[216:219], v161 offset:54272
	ds_read_b128 v[220:223], v161 offset:55296
	ds_read_b128 v[224:227], v161 offset:56320
	global_load_lds_dwordx4 v[148:149], off
	v_lshl_add_u64 v[148:149], v[152:153], 0, s[20:21]
	s_add_i32 m0, s34, 0x2000
	s_add_i32 s34, s92, s11
	global_load_lds_dwordx4 v[148:149], off
	v_lshl_add_u64 v[148:149], v[206:207], 0, s[20:21]
	s_mov_b32 m0, s34
	s_nop 0
	global_load_lds_dwordx4 v[148:149], off
	v_lshl_add_u64 v[148:149], v[228:229], 0, s[20:21]
	s_add_i32 m0, s34, 0x2000
	s_nop 0
	global_load_lds_dwordx4 v[148:149], off
	v_lshl_add_u64 v[148:149], v[230:231], 0, s[20:21]
	s_mov_b32 m0, s65
	s_nop 0
	global_load_lds_dwordx4 v[148:149], off
	v_lshl_add_u64 v[148:149], v[232:233], 0, s[20:21]
	s_mov_b32 m0, s66
	s_nop 0
	global_load_lds_dwordx4 v[148:149], off
	s_waitcnt vmcnt(8)
	s_waitcnt lgkmcnt(0)
	s_barrier
	s_setprio 1
	s_waitcnt lgkmcnt(0)
	v_mfma_f32_16x16x32_bf16 v[60:63], v[142:145], v[190:193], v[60:63]
	v_mfma_f32_16x16x32_bf16 v[52:55], v[166:169], v[190:193], v[52:55]
	v_mfma_f32_16x16x32_bf16 v[44:47], v[142:145], v[198:201], v[44:47]
	v_mfma_f32_16x16x32_bf16 v[36:39], v[166:169], v[198:201], v[36:39]
	v_mfma_f32_16x16x32_bf16 v[28:31], v[142:145], v[212:215], v[28:31]
	v_mfma_f32_16x16x32_bf16 v[20:23], v[166:169], v[212:215], v[20:23]
	v_mfma_f32_16x16x32_bf16 v[12:15], v[142:145], v[220:223], v[12:15]
	v_mfma_f32_16x16x32_bf16 v[4:7], v[166:169], v[220:223], v[4:7]
	v_mfma_f32_16x16x32_bf16 v[60:63], v[162:165], v[194:197], v[60:63]
	v_mfma_f32_16x16x32_bf16 v[52:55], v[170:173], v[194:197], v[52:55]
	v_mfma_f32_16x16x32_bf16 v[44:47], v[162:165], v[202:205], v[44:47]
	v_mfma_f32_16x16x32_bf16 v[36:39], v[170:173], v[202:205], v[36:39]
	v_mfma_f32_16x16x32_bf16 v[28:31], v[162:165], v[216:219], v[28:31]
	v_mfma_f32_16x16x32_bf16 v[20:23], v[170:173], v[216:219], v[20:23]
	v_mfma_f32_16x16x32_bf16 v[12:15], v[162:165], v[224:227], v[12:15]
	v_mfma_f32_16x16x32_bf16 v[4:7], v[170:173], v[224:227], v[4:7]
	s_setprio 0
	s_setprio 1
	v_mfma_f32_16x16x32_bf16 v[56:59], v[174:177], v[190:193], v[56:59]
	v_mfma_f32_16x16x32_bf16 v[48:51], v[182:185], v[190:193], v[48:51]
	v_mfma_f32_16x16x32_bf16 v[40:43], v[174:177], v[198:201], v[40:43]
	v_mfma_f32_16x16x32_bf16 v[32:35], v[182:185], v[198:201], v[32:35]
	v_mfma_f32_16x16x32_bf16 v[24:27], v[174:177], v[212:215], v[24:27]
	v_mfma_f32_16x16x32_bf16 v[16:19], v[182:185], v[212:215], v[16:19]
	v_mfma_f32_16x16x32_bf16 v[8:11], v[174:177], v[220:223], v[8:11]
	v_mfma_f32_16x16x32_bf16 v[0:3], v[182:185], v[220:223], v[0:3]
	v_mfma_f32_16x16x32_bf16 v[56:59], v[178:181], v[194:197], v[56:59]
	v_mfma_f32_16x16x32_bf16 v[48:51], v[186:189], v[194:197], v[48:51]
	v_mfma_f32_16x16x32_bf16 v[40:43], v[178:181], v[202:205], v[40:43]
	v_mfma_f32_16x16x32_bf16 v[32:35], v[186:189], v[202:205], v[32:35]
	v_mfma_f32_16x16x32_bf16 v[24:27], v[178:181], v[216:219], v[24:27]
	v_mfma_f32_16x16x32_bf16 v[16:19], v[186:189], v[216:219], v[16:19]
	v_mfma_f32_16x16x32_bf16 v[8:11], v[178:181], v[224:227], v[8:11]
	v_mfma_f32_16x16x32_bf16 v[0:3], v[186:189], v[224:227], v[0:3]
	s_setprio 0
	s_barrier
	s_add_u32 s30, s30, 0x100
	s_addc_u32 s31, s31, 0
	s_add_u32 s77, s77, 0x100
	s_addc_u32 s82, s82, 0
	s_cmp_ge_i32 s84, s67
	s_mov_b32 s34, s84
	s_cbranch_scc0 .LBB0_191
	s_branch .LBB0_192

; __device__ __forceinline__ u32x2 pack4(const f32x4 v) { u32x2 w; w.x = cvt_pk_bf16(v[0], v[1]); w.y = cvt_pk_bf16(v[2], v[3]); return w; }
;     __device__ __forceinline__ void operator()(const f32x4 (&acc)[2][2][4][2], const Unit& u, int wr, int wc, int fr, int fq) const {
;     ...
;         for (int ai = 0; ai < 2; ++ai)
; #pragma unroll
;             for (int m = 0; m < 4; ++m) {
;                 const int row = u.pm * BM + ai * HALF + wr * 64 + m * 16 + fr;
;                 const float rs = rsv[ai][m];
;                 u32x2 w[2];
; #pragma unroll
;                 for (int n = 0; n < 2; ++n) {
;                     const f32x4 g = acc[ai][0][m][n] * rs, up = acc[ai][1][m][n] * rs; f32x4 o;
; #pragma unroll
;                     for (int j = 0; j < 4; ++j) { const float e = __builtin_amdgcn_exp2f(-g[j] * kLog2e); o[j] = g[j] * up[j] * __builtin_amdgcn_rcpf(1.0f + e); }
;                     w[n] = pack4(o);
;                 }
;                 *(u32x4_*)(H + (size_t)row * 2816 + u.pn * 128 + wc * 32 + fq * 8) = (u32x4_){w[0].x, w[0].y, w[1].x, w[1].y};
.Lgu_rs_hit:
	s_and_b64 vcc, exec, s[38:39]
	v_mul_u32_u24_e32 v186, 0x1600, v162
	v_mov_b32_e32 v187, 0
	s_lshl_b32 s30, s72, 7
	s_ashr_i32 s31, s30, 31
	s_lshl_b64 s[30:31], s[30:31], 1
	v_lshl_add_u64 v[184:185], s[90:91], 0, v[186:187]
	v_lshl_add_u64 v[184:185], v[184:185], 0, s[30:31]
	v_lshl_add_u64 v[184:185], v[184:185], 0, s[18:19]
	v_lshl_add_u64 v[184:185], v[184:185], 0, v[208:209]
	s_mov_b32 s34, 0x16000
	s_mov_b32 s35, 0
	s_mov_b32 s30, 0x6e000
	s_mov_b32 s31, 0
	v_mul_f32_e32 v180, 0xbfb8aa3b, v164
	v_mul_f32_e32 v182, v164, v164
	v_rcp_f32_e32 v182, v182
	v_pk_mul_f32 v[168:169], v[120:121], v[180:181] op_sel_hi:[1,0]
	v_pk_mul_f32 v[170:171], v[122:123], v[180:181] op_sel_hi:[1,0]
	v_pk_mul_f32 v[172:173], v[116:117], v[180:181] op_sel_hi:[1,0]
	v_pk_mul_f32 v[174:175], v[118:119], v[180:181] op_sel_hi:[1,0]
	v_exp_f32_e32 v168, v168
	v_exp_f32_e32 v169, v169
	v_exp_f32_e32 v170, v170
	v_exp_f32_e32 v171, v171
	v_exp_f32_e32 v172, v172
	v_exp_f32_e32 v173, v173
	v_exp_f32_e32 v174, v174
	v_exp_f32_e32 v175, v175
	v_pk_mul_f32 v[120:121], v[120:121], v[124:125]
	v_pk_mul_f32 v[122:123], v[122:123], v[126:127]
	v_pk_mul_f32 v[116:117], v[116:117], v[112:113]
	v_pk_mul_f32 v[118:119], v[118:119], v[114:115]
	v_pk_fma_f32 v[168:169], v[168:169], v[182:183], v[182:183] op_sel_hi:[1,0,0]
	v_pk_fma_f32 v[170:171], v[170:171], v[182:183], v[182:183] op_sel_hi:[1,0,0]
	v_pk_fma_f32 v[172:173], v[172:173], v[182:183], v[182:183] op_sel_hi:[1,0,0]
	v_pk_fma_f32 v[174:175], v[174:175], v[182:183], v[182:183] op_sel_hi:[1,0,0]
	v_rcp_f32_e32 v168, v168
	v_rcp_f32_e32 v169, v169
	v_rcp_f32_e32 v170, v170
	v_rcp_f32_e32 v171, v171
	v_rcp_f32_e32 v172, v172
	v_rcp_f32_e32 v173, v173
	v_rcp_f32_e32 v174, v174
	v_rcp_f32_e32 v175, v175
	s_nop 0
	v_pk_mul_f32 v[120:121], v[120:121], v[168:169]
	v_pk_mul_f32 v[122:123], v[122:123], v[170:171]
	v_pk_mul_f32 v[116:117], v[116:117], v[172:173]
	v_pk_mul_f32 v[118:119], v[118:119], v[174:175]
	v_cvt_pk_bf16_f32 v176, v120, v121
	v_cvt_pk_bf16_f32 v177, v122, v123
	v_cvt_pk_bf16_f32 v178, v116, v117
	v_cvt_pk_bf16_f32 v179, v118, v119
	global_store_dwordx4 v[184:185], v[176:179], off
	v_lshl_add_u64 v[184:185], v[184:185], 0, s[34:35]
	v_mul_f32_e32 v180, 0xbfb8aa3b, v166
	v_mul_f32_e32 v182, v166, v166
	v_rcp_f32_e32 v182, v182
	v_pk_mul_f32 v[168:169], v[108:109], v[180:181] op_sel_hi:[1,0]
	v_pk_mul_f32 v[170:171], v[110:111], v[180:181] op_sel_hi:[1,0]
	v_pk_mul_f32 v[172:173], v[100:101], v[180:181] op_sel_hi:[1,0]
	v_pk_mul_f32 v[174:175], v[102:103], v[180:181] op_sel_hi:[1,0]
	v_exp_f32_e32 v168, v168
	v_exp_f32_e32 v169, v169
	v_exp_f32_e32 v170, v170
	v_exp_f32_e32 v171, v171
	v_exp_f32_e32 v172, v172
	v_exp_f32_e32 v173, v173
	v_exp_f32_e32 v174, v174
	v_exp_f32_e32 v175, v175
	v_pk_mul_f32 v[108:109], v[108:109], v[104:105]
	v_pk_mul_f32 v[110:111], v[110:111], v[106:107]
	v_pk_mul_f32 v[100:101], v[100:101], v[96:97]
	v_pk_mul_f32 v[102:103], v[102:103], v[98:99]
	v_pk_fma_f32 v[168:169], v[168:169], v[182:183], v[182:183] op_sel_hi:[1,0,0]
	v_pk_fma_f32 v[170:171], v[170:171], v[182:183], v[182:183] op_sel_hi:[1,0,0]
	v_pk_fma_f32 v[172:173], v[172:173], v[182:183], v[182:183] op_sel_hi:[1,0,0]
	v_pk_fma_f32 v[174:175], v[174:175], v[182:183], v[182:183] op_sel_hi:[1,0,0]
	v_rcp_f32_e32 v168, v168
	v_rcp_f32_e32 v169, v169
	v_rcp_f32_e32 v170, v170
	v_rcp_f32_e32 v171, v171
	v_rcp_f32_e32 v172, v172
	v_rcp_f32_e32 v173, v173
	v_rcp_f32_e32 v174, v174
	v_rcp_f32_e32 v175, v175
	s_nop 0
	v_pk_mul_f32 v[108:109], v[108:109], v[168:169]
	v_pk_mul_f32 v[110:111], v[110:111], v[170:171]
	v_pk_mul_f32 v[100:101], v[100:101], v[172:173]
	v_pk_mul_f32 v[102:103], v[102:103], v[174:175]
	v_cvt_pk_bf16_f32 v176, v108, v109
	v_cvt_pk_bf16_f32 v177, v110, v111
	v_cvt_pk_bf16_f32 v178, v100, v101
	v_cvt_pk_bf16_f32 v179, v102, v103
	global_store_dwordx4 v[184:185], v[176:179], off
	v_lshl_add_u64 v[184:185], v[184:185], 0, s[34:35]
	v_mul_f32_e32 v180, 0xbfb8aa3b, v160
	v_mul_f32_e32 v182, v160, v160
	v_rcp_f32_e32 v182, v182
	v_pk_mul_f32 v[168:169], v[92:93], v[180:181] op_sel_hi:[1,0]
	v_pk_mul_f32 v[170:171], v[94:95], v[180:181] op_sel_hi:[1,0]
	v_pk_mul_f32 v[172:173], v[84:85], v[180:181] op_sel_hi:[1,0]
	v_pk_mul_f32 v[174:175], v[86:87], v[180:181] op_sel_hi:[1,0]
	v_exp_f32_e32 v168, v168
	v_exp_f32_e32 v169, v169
	v_exp_f32_e32 v170, v170
	v_exp_f32_e32 v171, v171
	v_exp_f32_e32 v172, v172
	v_exp_f32_e32 v173, v173
	v_exp_f32_e32 v174, v174
	v_exp_f32_e32 v175, v175
	v_pk_mul_f32 v[92:93], v[92:93], v[88:89]
	v_pk_mul_f32 v[94:95], v[94:95], v[90:91]
	v_pk_mul_f32 v[84:85], v[84:85], v[80:81]
	v_pk_mul_f32 v[86:87], v[86:87], v[82:83]
	v_pk_fma_f32 v[168:169], v[168:169], v[182:183], v[182:183] op_sel_hi:[1,0,0]
	v_pk_fma_f32 v[170:171], v[170:171], v[182:183], v[182:183] op_sel_hi:[1,0,0]
	v_pk_fma_f32 v[172:173], v[172:173], v[182:183], v[182:183] op_sel_hi:[1,0,0]
	v_pk_fma_f32 v[174:175], v[174:175], v[182:183], v[182:183] op_sel_hi:[1,0,0]
	v_rcp_f32_e32 v168, v168
	v_rcp_f32_e32 v169, v169
	v_rcp_f32_e32 v170, v170
	v_rcp_f32_e32 v171, v171
	v_rcp_f32_e32 v172, v172
	v_rcp_f32_e32 v173, v173
	v_rcp_f32_e32 v174, v174
	v_rcp_f32_e32 v175, v175
	s_nop 0
	v_pk_mul_f32 v[92:93], v[92:93], v[168:169]
	v_pk_mul_f32 v[94:95], v[94:95], v[170:171]
	v_pk_mul_f32 v[84:85], v[84:85], v[172:173]
	v_pk_mul_f32 v[86:87], v[86:87], v[174:175]
	v_cvt_pk_bf16_f32 v176, v92, v93
	v_cvt_pk_bf16_f32 v177, v94, v95
	v_cvt_pk_bf16_f32 v178, v84, v85
	v_cvt_pk_bf16_f32 v179, v86, v87
	global_store_dwordx4 v[184:185], v[176:179], off
	v_lshl_add_u64 v[184:185], v[184:185], 0, s[34:35]
; __device__ __forceinline__ u32x2 pack4(const f32x4 v) { u32x2 w; w.x = cvt_pk_bf16(v[0], v[1]); w.y = cvt_pk_bf16(v[2], v[3]); return w; }
;     __device__ __forceinline__ void operator()(const f32x4 (&acc)[2][2][4][2], const Unit& u, int wr, int wc, int fr, int fq) const {
;     ...
;         for (int ai = 0; ai < 2; ++ai)
; #pragma unroll
;             for (int m = 0; m < 4; ++m) {
;                 const int row = u.pm * BM + ai * HALF + wr * 64 + m * 16 + fr;
;                 const float rs = rsv[ai][m];
;                 u32x2 w[2];
; #pragma unroll
;                 for (int n = 0; n < 2; ++n) {
;                     const f32x4 g = acc[ai][0][m][n] * rs, up = acc[ai][1][m][n] * rs; f32x4 o;
; #pragma unroll
;                     for (int j = 0; j < 4; ++j) { const float e = __builtin_amdgcn_exp2f(-g[j] * kLog2e); o[j] = g[j] * up[j] * __builtin_amdgcn_rcpf(1.0f + e); }
;                     w[n] = pack4(o);
;                 }
;                 *(u32x4_*)(H + (size_t)row * 2816 + u.pn * 128 + wc * 32 + fq * 8) = (u32x4_){w[0].x, w[0].y, w[1].x, w[1].y};
	v_mul_f32_e32 v180, 0xbfb8aa3b, v158
	v_mul_f32_e32 v182, v158, v158
	v_rcp_f32_e32 v182, v182
	v_pk_mul_f32 v[168:169], v[76:77], v[180:181] op_sel_hi:[1,0]
	v_pk_mul_f32 v[170:171], v[78:79], v[180:181] op_sel_hi:[1,0]
	v_pk_mul_f32 v[172:173], v[68:69], v[180:181] op_sel_hi:[1,0]
	v_pk_mul_f32 v[174:175], v[70:71], v[180:181] op_sel_hi:[1,0]
	v_exp_f32_e32 v168, v168
	v_exp_f32_e32 v169, v169
	v_exp_f32_e32 v170, v170
	v_exp_f32_e32 v171, v171
	v_exp_f32_e32 v172, v172
	v_exp_f32_e32 v173, v173
	v_exp_f32_e32 v174, v174
	v_exp_f32_e32 v175, v175
	v_pk_mul_f32 v[76:77], v[76:77], v[72:73]
	v_pk_mul_f32 v[78:79], v[78:79], v[74:75]
	v_pk_mul_f32 v[68:69], v[68:69], v[64:65]
	v_pk_mul_f32 v[70:71], v[70:71], v[66:67]
	v_pk_fma_f32 v[168:169], v[168:169], v[182:183], v[182:183] op_sel_hi:[1,0,0]
	v_pk_fma_f32 v[170:171], v[170:171], v[182:183], v[182:183] op_sel_hi:[1,0,0]
	v_pk_fma_f32 v[172:173], v[172:173], v[182:183], v[182:183] op_sel_hi:[1,0,0]
	v_pk_fma_f32 v[174:175], v[174:175], v[182:183], v[182:183] op_sel_hi:[1,0,0]
	v_rcp_f32_e32 v168, v168
	v_rcp_f32_e32 v169, v169
	v_rcp_f32_e32 v170, v170
	v_rcp_f32_e32 v171, v171
	v_rcp_f32_e32 v172, v172
	v_rcp_f32_e32 v173, v173
	v_rcp_f32_e32 v174, v174
	v_rcp_f32_e32 v175, v175
	s_nop 0
	v_pk_mul_f32 v[76:77], v[76:77], v[168:169]
	v_pk_mul_f32 v[78:79], v[78:79], v[170:171]
	v_pk_mul_f32 v[68:69], v[68:69], v[172:173]
	v_pk_mul_f32 v[70:71], v[70:71], v[174:175]
	v_cvt_pk_bf16_f32 v176, v76, v77
	v_cvt_pk_bf16_f32 v177, v78, v79
	v_cvt_pk_bf16_f32 v178, v68, v69
	v_cvt_pk_bf16_f32 v179, v70, v71
	global_store_dwordx4 v[184:185], v[176:179], off
	v_lshl_add_u64 v[184:185], v[184:185], 0, s[30:31]
	v_mul_f32_e32 v180, 0xbfb8aa3b, v156
	v_mul_f32_e32 v182, v156, v156
	v_rcp_f32_e32 v182, v182
	v_pk_mul_f32 v[168:169], v[60:61], v[180:181] op_sel_hi:[1,0]
	v_pk_mul_f32 v[170:171], v[62:63], v[180:181] op_sel_hi:[1,0]
	v_pk_mul_f32 v[172:173], v[52:53], v[180:181] op_sel_hi:[1,0]
	v_pk_mul_f32 v[174:175], v[54:55], v[180:181] op_sel_hi:[1,0]
	v_exp_f32_e32 v168, v168
	v_exp_f32_e32 v169, v169
	v_exp_f32_e32 v170, v170
	v_exp_f32_e32 v171, v171
	v_exp_f32_e32 v172, v172
	v_exp_f32_e32 v173, v173
	v_exp_f32_e32 v174, v174
	v_exp_f32_e32 v175, v175
	v_pk_mul_f32 v[60:61], v[60:61], v[56:57]
	v_pk_mul_f32 v[62:63], v[62:63], v[58:59]
	v_pk_mul_f32 v[52:53], v[52:53], v[48:49]
	v_pk_mul_f32 v[54:55], v[54:55], v[50:51]
	v_pk_fma_f32 v[168:169], v[168:169], v[182:183], v[182:183] op_sel_hi:[1,0,0]
	v_pk_fma_f32 v[170:171], v[170:171], v[182:183], v[182:183] op_sel_hi:[1,0,0]
	v_pk_fma_f32 v[172:173], v[172:173], v[182:183], v[182:183] op_sel_hi:[1,0,0]
	v_pk_fma_f32 v[174:175], v[174:175], v[182:183], v[182:183] op_sel_hi:[1,0,0]
	v_rcp_f32_e32 v168, v168
	v_rcp_f32_e32 v169, v169
	v_rcp_f32_e32 v170, v170
	v_rcp_f32_e32 v171, v171
	v_rcp_f32_e32 v172, v172
	v_rcp_f32_e32 v173, v173
	v_rcp_f32_e32 v174, v174
	v_rcp_f32_e32 v175, v175
	s_nop 0
	v_pk_mul_f32 v[60:61], v[60:61], v[168:169]
	v_pk_mul_f32 v[62:63], v[62:63], v[170:171]
	v_pk_mul_f32 v[52:53], v[52:53], v[172:173]
	v_pk_mul_f32 v[54:55], v[54:55], v[174:175]
	v_cvt_pk_bf16_f32 v176, v60, v61
	v_cvt_pk_bf16_f32 v177, v62, v63
	v_cvt_pk_bf16_f32 v178, v52, v53
	v_cvt_pk_bf16_f32 v179, v54, v55
	global_store_dwordx4 v[184:185], v[176:179], off
	v_lshl_add_u64 v[184:185], v[184:185], 0, s[34:35]
	v_mul_f32_e32 v180, 0xbfb8aa3b, v154
	v_mul_f32_e32 v182, v154, v154
	v_rcp_f32_e32 v182, v182
	v_pk_mul_f32 v[168:169], v[44:45], v[180:181] op_sel_hi:[1,0]
	v_pk_mul_f32 v[170:171], v[46:47], v[180:181] op_sel_hi:[1,0]
	v_pk_mul_f32 v[172:173], v[36:37], v[180:181] op_sel_hi:[1,0]
	v_pk_mul_f32 v[174:175], v[38:39], v[180:181] op_sel_hi:[1,0]
	v_exp_f32_e32 v168, v168
	v_exp_f32_e32 v169, v169
	v_exp_f32_e32 v170, v170
	v_exp_f32_e32 v171, v171
	v_exp_f32_e32 v172, v172
	v_exp_f32_e32 v173, v173
	v_exp_f32_e32 v174, v174
	v_exp_f32_e32 v175, v175
	v_pk_mul_f32 v[44:45], v[44:45], v[40:41]
	v_pk_mul_f32 v[46:47], v[46:47], v[42:43]
	v_pk_mul_f32 v[36:37], v[36:37], v[32:33]
	v_pk_mul_f32 v[38:39], v[38:39], v[34:35]
	v_pk_fma_f32 v[168:169], v[168:169], v[182:183], v[182:183] op_sel_hi:[1,0,0]
	v_pk_fma_f32 v[170:171], v[170:171], v[182:183], v[182:183] op_sel_hi:[1,0,0]
; __device__ __forceinline__ u32x2 pack4(const f32x4 v) { u32x2 w; w.x = cvt_pk_bf16(v[0], v[1]); w.y = cvt_pk_bf16(v[2], v[3]); return w; }
; #define PG8_BAR __builtin_amdgcn_s_barrier()
;     __device__ __forceinline__ void operator()(const f32x4 (&acc)[2][2][4][2], const Unit& u, int wr, int wc, int fr, int fq) const {
;     ...
;         for (int ai = 0; ai < 2; ++ai)
; #pragma unroll
;             for (int m = 0; m < 4; ++m) {
;                 const int row = u.pm * BM + ai * HALF + wr * 64 + m * 16 + fr;
;                 const float rs = rsv[ai][m];
;                 u32x2 w[2];
; #pragma unroll
;                 for (int n = 0; n < 2; ++n) {
;                     const f32x4 g = acc[ai][0][m][n] * rs, up = acc[ai][1][m][n] * rs; f32x4 o;
; #pragma unroll
;                     for (int j = 0; j < 4; ++j) { const float e = __builtin_amdgcn_exp2f(-g[j] * kLog2e); o[j] = g[j] * up[j] * __builtin_amdgcn_rcpf(1.0f + e); }
;                     w[n] = pack4(o);
;                 }
;                 *(u32x4_*)(H + (size_t)row * 2816 + u.pn * 128 + wc * 32 + fq * 8) = (u32x4_){w[0].x, w[0].y, w[1].x, w[1].y};
; template <class Epi, class Sched, bool ALIGN_EPI = false, bool SP2 = false>
; __device__ __forceinline__ void gemm_phase(PG8_LAS unsigned char* lds, const Gemm g, const Sched& S, const Epi& E) {
;     ...
;         if (!has_next) break;
; #pragma unroll
;         for (int a = 0; a < 2; ++a)
; #pragma unroll
;             for (int b = 0; b < 2; ++b)
; #pragma unroll
;                 for (int m = 0; m < 4; ++m)
; #pragma unroll
;                     for (int n = 0; n < 2; ++n) acc[a][b][m][n] = (f32x4){0.f, 0.f, 0.f, 0.f};
;         cur = nxt; cA = nA; cB = nB; ++ui;
;         if constexpr (ALIGN_EPI) { if (wr == 1) PG8_BAR; }
	v_pk_fma_f32 v[172:173], v[172:173], v[182:183], v[182:183] op_sel_hi:[1,0,0]
	v_pk_fma_f32 v[174:175], v[174:175], v[182:183], v[182:183] op_sel_hi:[1,0,0]
	v_rcp_f32_e32 v168, v168
	v_rcp_f32_e32 v169, v169
	v_rcp_f32_e32 v170, v170
	v_rcp_f32_e32 v171, v171
	v_rcp_f32_e32 v172, v172
	v_rcp_f32_e32 v173, v173
	v_rcp_f32_e32 v174, v174
	v_rcp_f32_e32 v175, v175
	s_nop 0
	v_pk_mul_f32 v[44:45], v[44:45], v[168:169]
	v_pk_mul_f32 v[46:47], v[46:47], v[170:171]
	v_pk_mul_f32 v[36:37], v[36:37], v[172:173]
	v_pk_mul_f32 v[38:39], v[38:39], v[174:175]
	v_cvt_pk_bf16_f32 v176, v44, v45
	v_cvt_pk_bf16_f32 v177, v46, v47
	v_cvt_pk_bf16_f32 v178, v36, v37
	v_cvt_pk_bf16_f32 v179, v38, v39
	global_store_dwordx4 v[184:185], v[176:179], off
	v_lshl_add_u64 v[184:185], v[184:185], 0, s[34:35]
	v_mul_f32_e32 v180, 0xbfb8aa3b, v150
	v_mul_f32_e32 v182, v150, v150
	v_rcp_f32_e32 v182, v182
	v_pk_mul_f32 v[168:169], v[28:29], v[180:181] op_sel_hi:[1,0]
	v_pk_mul_f32 v[170:171], v[30:31], v[180:181] op_sel_hi:[1,0]
	v_pk_mul_f32 v[172:173], v[20:21], v[180:181] op_sel_hi:[1,0]
	v_pk_mul_f32 v[174:175], v[22:23], v[180:181] op_sel_hi:[1,0]
	v_exp_f32_e32 v168, v168
	v_exp_f32_e32 v169, v169
	v_exp_f32_e32 v170, v170
	v_exp_f32_e32 v171, v171
	v_exp_f32_e32 v172, v172
	v_exp_f32_e32 v173, v173
	v_exp_f32_e32 v174, v174
	v_exp_f32_e32 v175, v175
	v_pk_mul_f32 v[28:29], v[28:29], v[24:25]
	v_pk_mul_f32 v[30:31], v[30:31], v[26:27]
	v_pk_mul_f32 v[20:21], v[20:21], v[16:17]
	v_pk_mul_f32 v[22:23], v[22:23], v[18:19]
	v_pk_fma_f32 v[168:169], v[168:169], v[182:183], v[182:183] op_sel_hi:[1,0,0]
	v_pk_fma_f32 v[170:171], v[170:171], v[182:183], v[182:183] op_sel_hi:[1,0,0]
	v_pk_fma_f32 v[172:173], v[172:173], v[182:183], v[182:183] op_sel_hi:[1,0,0]
	v_pk_fma_f32 v[174:175], v[174:175], v[182:183], v[182:183] op_sel_hi:[1,0,0]
	v_rcp_f32_e32 v168, v168
	v_rcp_f32_e32 v169, v169
	v_rcp_f32_e32 v170, v170
	v_rcp_f32_e32 v171, v171
	v_rcp_f32_e32 v172, v172
	v_rcp_f32_e32 v173, v173
	v_rcp_f32_e32 v174, v174
	v_rcp_f32_e32 v175, v175
	s_nop 0
	v_pk_mul_f32 v[28:29], v[28:29], v[168:169]
	v_pk_mul_f32 v[30:31], v[30:31], v[170:171]
	v_pk_mul_f32 v[20:21], v[20:21], v[172:173]
	v_pk_mul_f32 v[22:23], v[22:23], v[174:175]
	v_cvt_pk_bf16_f32 v176, v28, v29
	v_cvt_pk_bf16_f32 v177, v30, v31
	v_cvt_pk_bf16_f32 v178, v20, v21
	v_cvt_pk_bf16_f32 v179, v22, v23
	global_store_dwordx4 v[184:185], v[176:179], off
	v_lshl_add_u64 v[184:185], v[184:185], 0, s[34:35]
	v_mul_f32_e32 v180, 0xbfb8aa3b, v146
	v_mul_f32_e32 v182, v146, v146
	v_rcp_f32_e32 v182, v182
	v_pk_mul_f32 v[168:169], v[12:13], v[180:181] op_sel_hi:[1,0]
	v_pk_mul_f32 v[170:171], v[14:15], v[180:181] op_sel_hi:[1,0]
	v_pk_mul_f32 v[172:173], v[4:5], v[180:181] op_sel_hi:[1,0]
	v_pk_mul_f32 v[174:175], v[6:7], v[180:181] op_sel_hi:[1,0]
	v_exp_f32_e32 v168, v168
	v_exp_f32_e32 v169, v169
	v_exp_f32_e32 v170, v170
	v_exp_f32_e32 v171, v171
	v_exp_f32_e32 v172, v172
	v_exp_f32_e32 v173, v173
	v_exp_f32_e32 v174, v174
	v_exp_f32_e32 v175, v175
	v_pk_mul_f32 v[12:13], v[12:13], v[8:9]
	v_pk_mul_f32 v[14:15], v[14:15], v[10:11]
	v_pk_mul_f32 v[4:5], v[4:5], v[0:1]
	v_pk_mul_f32 v[6:7], v[6:7], v[2:3]
	v_pk_fma_f32 v[168:169], v[168:169], v[182:183], v[182:183] op_sel_hi:[1,0,0]
	v_pk_fma_f32 v[170:171], v[170:171], v[182:183], v[182:183] op_sel_hi:[1,0,0]
	v_pk_fma_f32 v[172:173], v[172:173], v[182:183], v[182:183] op_sel_hi:[1,0,0]
	v_pk_fma_f32 v[174:175], v[174:175], v[182:183], v[182:183] op_sel_hi:[1,0,0]
	v_rcp_f32_e32 v168, v168
	v_rcp_f32_e32 v169, v169
	v_rcp_f32_e32 v170, v170
	v_rcp_f32_e32 v171, v171
	v_rcp_f32_e32 v172, v172
	v_rcp_f32_e32 v173, v173
	v_rcp_f32_e32 v174, v174
	v_rcp_f32_e32 v175, v175
	s_nop 0
	v_pk_mul_f32 v[12:13], v[12:13], v[168:169]
	v_pk_mul_f32 v[14:15], v[14:15], v[170:171]
	v_pk_mul_f32 v[4:5], v[4:5], v[172:173]
	v_pk_mul_f32 v[6:7], v[6:7], v[174:175]
	v_cvt_pk_bf16_f32 v176, v12, v13
	v_cvt_pk_bf16_f32 v177, v14, v15
	v_cvt_pk_bf16_f32 v178, v4, v5
	v_cvt_pk_bf16_f32 v179, v6, v7
	global_store_dwordx4 v[184:185], v[176:179], off
	s_mov_b64 s[30:31], -1
	s_cbranch_vccnz .LBB0_182
	s_mov_b32 s92, 2
	s_andn2_b64 vcc, exec, s[28:29]
	s_cbranch_vccnz .LBB0_181
	s_mov_b32 s92, 3
	s_branch .LBB0_181
